# phase 11a transpose-reduce: 28 ds_bpermute lane exchanges (xor 4/2/1) with their two selects and add replaced by v_add_f32_dpp (row_shl/shr:4 bank-masked, quad_perm) - same sums, no LDS round trips
# baseline (speedup 1.0000x reference)
.LBB0_913:
	s_waitcnt vmcnt(1)
	ds_bpermute_b32 v65, v147, v181
	v_add_u32_e32 v180, s20, v64
	ds_bpermute_b32 v66, v170, v181
	v_add_u32_e32 v167, s22, v64
	v_add_u32_e32 v166, s23, v64
	s_waitcnt lgkmcnt(1)
	v_lshl_or_b32 v64, v65, 11, v145
	ds_bpermute_b32 v65, v171, v181
	ds_bpermute_b32 v67, v172, v181
	s_waitcnt lgkmcnt(2)
	v_lshl_or_b32 v66, v66, 11, v145
	global_load_dwordx4 v[124:127], v64, s[16:17]
	global_load_dwordx4 v[120:123], v66, s[16:17]
	v_cmp_gt_u32_e64 s[10:11], s3, v180
	s_waitcnt lgkmcnt(1)
	v_lshl_or_b32 v64, v65, 11, v145
	ds_bpermute_b32 v65, v173, v181
	s_waitcnt lgkmcnt(1)
	v_lshl_or_b32 v66, v67, 11, v145
	ds_bpermute_b32 v67, v174, v181
	global_load_dwordx4 v[116:119], v64, s[16:17]
	global_load_dwordx4 v[112:115], v66, s[16:17]
	v_cndmask_b32_e64 v148, v146, v180, s[10:11]
	s_waitcnt lgkmcnt(1)
	v_lshl_or_b32 v64, v65, 11, v145
	ds_bpermute_b32 v65, v175, v181
	s_waitcnt lgkmcnt(1)
	v_lshl_or_b32 v66, v67, 11, v145
	ds_bpermute_b32 v67, v176, v181
	global_load_dwordx4 v[108:111], v64, s[16:17]
	global_load_dwordx4 v[104:107], v66, s[16:17]
	v_cmp_gt_u32_e64 s[12:13], s3, v167
	s_waitcnt lgkmcnt(1)
	v_lshl_or_b32 v64, v65, 11, v145
	s_waitcnt vmcnt(6)
	ds_bpermute_b32 v65, v147, v157
	s_waitcnt lgkmcnt(1)
	v_lshl_or_b32 v66, v67, 11, v145
	ds_bpermute_b32 v67, v170, v157
	global_load_dwordx4 v[100:103], v64, s[16:17]
	global_load_dwordx4 v[96:99], v66, s[16:17]
	v_lshlrev_b64 v[128:129], 11, v[148:149]
	s_waitcnt lgkmcnt(1)
	v_lshl_or_b32 v64, v65, 11, v145
	ds_bpermute_b32 v65, v171, v157
	s_waitcnt lgkmcnt(1)
	v_lshl_or_b32 v66, v67, 11, v145
	ds_bpermute_b32 v67, v172, v157
	global_load_dwordx4 v[92:95], v64, s[16:17]
	global_load_dwordx4 v[88:91], v66, s[16:17]
	v_cndmask_b32_e64 v148, v146, v167, s[12:13]
	s_waitcnt lgkmcnt(1)
	v_lshl_or_b32 v64, v65, 11, v145
	ds_bpermute_b32 v65, v173, v157
	s_waitcnt lgkmcnt(1)
	v_lshl_or_b32 v66, v67, 11, v145
	ds_bpermute_b32 v67, v174, v157
	global_load_dwordx4 v[84:87], v64, s[16:17]
	global_load_dwordx4 v[80:83], v66, s[16:17]
	ds_bpermute_b32 v66, v176, v157
	s_waitcnt lgkmcnt(2)
	v_lshl_or_b32 v64, v65, 11, v145
	ds_bpermute_b32 v65, v175, v157
	v_lshlrev_b64 v[182:183], 9, v[148:149]
	s_waitcnt lgkmcnt(2)
	v_lshl_or_b32 v67, v67, 11, v145
	global_load_dwordx4 v[76:79], v64, s[16:17]
	global_load_dwordx4 v[72:75], v67, s[16:17]
	v_lshl_add_u64 v[128:129], v[150:151], 0, v[128:129]
	s_waitcnt lgkmcnt(0)
	v_lshl_or_b32 v64, v65, 11, v145
	v_lshl_or_b32 v65, v66, 11, v145
	v_lshl_add_u64 v[182:183], v[152:153], 0, v[182:183]
	global_load_dwordx4 v[68:71], v64, s[16:17]
	s_nop 0
	global_load_dwordx4 v[64:67], v65, s[16:17]
	s_nop 0
	global_load_dwordx4 v[132:135], v[128:129], off offset:16
	s_nop 0
	global_load_dwordx4 v[128:131], v[128:129], off
	s_nop 0
	global_load_dword v181, v[182:183], off
	global_load_dword v167, v[182:183], off offset:256
	v_cvt_pk_f32_fp8_e32 v[182:183], v60
	v_cvt_pk_f32_fp8_sdwa v[184:185], v60 src0_sel:WORD_1
	v_cvt_pk_f32_fp8_e32 v[186:187], v61
	v_cvt_pk_f32_fp8_sdwa v[60:61], v61 src0_sel:WORD_1
	v_pk_fma_f32 v[182:183], v[182:183], v[158:159], 0 op_sel_hi:[1,1,0]
	v_cmp_gt_u32_e64 s[12:13], s3, v166
	v_pk_fma_f32 v[182:183], v[184:185], v[160:161], v[182:183]
	v_cvt_pk_f32_fp8_sdwa v[184:185], v62 src0_sel:WORD_1
	v_pk_fma_f32 v[182:183], v[186:187], v[162:163], v[182:183]
	v_cvt_pk_f32_fp8_e32 v[186:187], v63
	v_pk_fma_f32 v[60:61], v[60:61], v[164:165], v[182:183]
	v_cvt_pk_f32_fp8_e32 v[182:183], v62
	v_cvt_pk_f32_fp8_sdwa v[62:63], v63 src0_sel:WORD_1
	v_pk_fma_f32 v[60:61], v[182:183], v[140:141], v[60:61]
	s_nop 0
	v_pk_fma_f32 v[60:61], v[184:185], v[136:137], v[60:61]
	v_cvt_pk_f32_fp8_e32 v[182:183], v57
	v_pk_fma_f32 v[60:61], v[186:187], v[142:143], v[60:61]
	s_nop 0
	v_pk_fma_f32 v[60:61], v[62:63], v[138:139], v[60:61]
	v_cvt_pk_f32_fp8_sdwa v[62:63], v56 src0_sel:WORD_1
	v_add_f32_e32 v157, v60, v61
	v_cvt_pk_f32_fp8_e32 v[60:61], v56
	v_cvt_pk_f32_fp8_sdwa v[56:57], v57 src0_sel:WORD_1
	v_pk_fma_f32 v[60:61], v[60:61], v[158:159], 0 op_sel_hi:[1,1,0]
	s_nop 0
	v_pk_fma_f32 v[60:61], v[62:63], v[160:161], v[60:61]
	v_cvt_pk_f32_fp8_sdwa v[62:63], v58 src0_sel:WORD_1
	v_pk_fma_f32 v[60:61], v[182:183], v[162:163], v[60:61]
	v_cvt_pk_f32_fp8_e32 v[182:183], v59
	v_pk_fma_f32 v[56:57], v[56:57], v[164:165], v[60:61]
	v_cvt_pk_f32_fp8_e32 v[60:61], v58
	v_cvt_pk_f32_fp8_sdwa v[58:59], v59 src0_sel:WORD_1
	v_pk_fma_f32 v[56:57], v[60:61], v[140:141], v[56:57]
	s_nop 0
	v_pk_fma_f32 v[56:57], v[62:63], v[136:137], v[56:57]
	v_cvt_pk_f32_fp8_e32 v[60:61], v53
	v_pk_fma_f32 v[56:57], v[182:183], v[142:143], v[56:57]
	s_nop 0
	v_pk_fma_f32 v[56:57], v[58:59], v[138:139], v[56:57]
	v_cvt_pk_f32_fp8_sdwa v[58:59], v52 src0_sel:WORD_1
	v_add_f32_e32 v62, v56, v57
	v_cvt_pk_f32_fp8_e32 v[56:57], v52
	v_cvt_pk_f32_fp8_sdwa v[52:53], v53 src0_sel:WORD_1
	v_pk_fma_f32 v[56:57], v[56:57], v[158:159], 0 op_sel_hi:[1,1,0]
	s_nop 0
	v_pk_fma_f32 v[56:57], v[58:59], v[160:161], v[56:57]
	v_cvt_pk_f32_fp8_sdwa v[58:59], v54 src0_sel:WORD_1
	v_pk_fma_f32 v[56:57], v[60:61], v[162:163], v[56:57]
	v_cvt_pk_f32_fp8_e32 v[60:61], v55
	v_pk_fma_f32 v[52:53], v[52:53], v[164:165], v[56:57]
	v_cvt_pk_f32_fp8_e32 v[56:57], v54
	v_cvt_pk_f32_fp8_sdwa v[54:55], v55 src0_sel:WORD_1
	v_pk_fma_f32 v[52:53], v[56:57], v[140:141], v[52:53]
	s_nop 0
	v_pk_fma_f32 v[52:53], v[58:59], v[136:137], v[52:53]
	v_cvt_pk_f32_fp8_e32 v[56:57], v49
	v_pk_fma_f32 v[52:53], v[60:61], v[142:143], v[52:53]
	s_nop 0
	v_pk_fma_f32 v[52:53], v[54:55], v[138:139], v[52:53]
	v_cvt_pk_f32_fp8_sdwa v[54:55], v48 src0_sel:WORD_1
	v_add_f32_e32 v58, v52, v53
	v_cvt_pk_f32_fp8_e32 v[52:53], v48
	v_cvt_pk_f32_fp8_sdwa v[48:49], v49 src0_sel:WORD_1
	v_pk_fma_f32 v[52:53], v[52:53], v[158:159], 0 op_sel_hi:[1,1,0]
	s_nop 0
	v_pk_fma_f32 v[52:53], v[54:55], v[160:161], v[52:53]
	v_cvt_pk_f32_fp8_sdwa v[54:55], v50 src0_sel:WORD_1
	v_pk_fma_f32 v[52:53], v[56:57], v[162:163], v[52:53]
	v_cvt_pk_f32_fp8_e32 v[56:57], v51
	v_pk_fma_f32 v[48:49], v[48:49], v[164:165], v[52:53]
	v_cvt_pk_f32_fp8_e32 v[52:53], v50
	v_cvt_pk_f32_fp8_sdwa v[50:51], v51 src0_sel:WORD_1
	v_pk_fma_f32 v[48:49], v[52:53], v[140:141], v[48:49]
	s_nop 0
	v_pk_fma_f32 v[48:49], v[54:55], v[136:137], v[48:49]
	v_cvt_pk_f32_fp8_e32 v[52:53], v45
	v_pk_fma_f32 v[48:49], v[56:57], v[142:143], v[48:49]
	s_nop 0
	v_pk_fma_f32 v[48:49], v[50:51], v[138:139], v[48:49]
	v_cvt_pk_f32_fp8_sdwa v[50:51], v44 src0_sel:WORD_1
	v_add_f32_e32 v54, v48, v49
	v_cvt_pk_f32_fp8_e32 v[48:49], v44
	v_cvt_pk_f32_fp8_sdwa v[44:45], v45 src0_sel:WORD_1
	v_pk_fma_f32 v[48:49], v[48:49], v[158:159], 0 op_sel_hi:[1,1,0]
	s_nop 0
	v_pk_fma_f32 v[48:49], v[50:51], v[160:161], v[48:49]
	v_cvt_pk_f32_fp8_sdwa v[50:51], v46 src0_sel:WORD_1
	v_pk_fma_f32 v[48:49], v[52:53], v[162:163], v[48:49]
	v_cvt_pk_f32_fp8_e32 v[52:53], v47
	v_pk_fma_f32 v[44:45], v[44:45], v[164:165], v[48:49]
	v_cvt_pk_f32_fp8_e32 v[48:49], v46
	v_cvt_pk_f32_fp8_sdwa v[46:47], v47 src0_sel:WORD_1
	v_pk_fma_f32 v[44:45], v[48:49], v[140:141], v[44:45]
	s_nop 0
	v_pk_fma_f32 v[44:45], v[50:51], v[136:137], v[44:45]
	v_cvt_pk_f32_fp8_e32 v[48:49], v41
	v_pk_fma_f32 v[44:45], v[52:53], v[142:143], v[44:45]
	s_nop 0
	v_pk_fma_f32 v[44:45], v[46:47], v[138:139], v[44:45]
	v_cvt_pk_f32_fp8_sdwa v[46:47], v40 src0_sel:WORD_1
	v_add_f32_e32 v50, v44, v45
	v_cvt_pk_f32_fp8_e32 v[44:45], v40
	v_cvt_pk_f32_fp8_sdwa v[40:41], v41 src0_sel:WORD_1
	v_pk_fma_f32 v[44:45], v[44:45], v[158:159], 0 op_sel_hi:[1,1,0]
	s_nop 0
	v_pk_fma_f32 v[44:45], v[46:47], v[160:161], v[44:45]
	v_cvt_pk_f32_fp8_sdwa v[46:47], v42 src0_sel:WORD_1
	v_pk_fma_f32 v[44:45], v[48:49], v[162:163], v[44:45]
	v_cvt_pk_f32_fp8_e32 v[48:49], v43
	v_pk_fma_f32 v[40:41], v[40:41], v[164:165], v[44:45]
	v_cvt_pk_f32_fp8_e32 v[44:45], v42
	v_cvt_pk_f32_fp8_sdwa v[42:43], v43 src0_sel:WORD_1
	v_pk_fma_f32 v[40:41], v[44:45], v[140:141], v[40:41]
	s_nop 0
	v_pk_fma_f32 v[40:41], v[46:47], v[136:137], v[40:41]
	v_cvt_pk_f32_fp8_e32 v[44:45], v37
	v_pk_fma_f32 v[40:41], v[48:49], v[142:143], v[40:41]
	s_nop 0
	v_pk_fma_f32 v[40:41], v[42:43], v[138:139], v[40:41]
	v_cvt_pk_f32_fp8_sdwa v[42:43], v36 src0_sel:WORD_1
	v_add_f32_e32 v46, v40, v41
	v_cvt_pk_f32_fp8_e32 v[40:41], v36
	v_cvt_pk_f32_fp8_sdwa v[36:37], v37 src0_sel:WORD_1
	v_pk_fma_f32 v[40:41], v[40:41], v[158:159], 0 op_sel_hi:[1,1,0]
	s_nop 0
	v_pk_fma_f32 v[40:41], v[42:43], v[160:161], v[40:41]
	v_cvt_pk_f32_fp8_sdwa v[42:43], v38 src0_sel:WORD_1
	v_pk_fma_f32 v[40:41], v[44:45], v[162:163], v[40:41]
	v_cvt_pk_f32_fp8_e32 v[44:45], v39
	v_pk_fma_f32 v[36:37], v[36:37], v[164:165], v[40:41]
	v_cvt_pk_f32_fp8_e32 v[40:41], v38
	v_cvt_pk_f32_fp8_sdwa v[38:39], v39 src0_sel:WORD_1
	v_pk_fma_f32 v[36:37], v[40:41], v[140:141], v[36:37]
	s_nop 0
	v_pk_fma_f32 v[36:37], v[42:43], v[136:137], v[36:37]
	v_cvt_pk_f32_fp8_e32 v[40:41], v33
	v_pk_fma_f32 v[36:37], v[44:45], v[142:143], v[36:37]
	s_nop 0
	v_pk_fma_f32 v[36:37], v[38:39], v[138:139], v[36:37]
	v_cvt_pk_f32_fp8_sdwa v[38:39], v32 src0_sel:WORD_1
	v_add_f32_e32 v42, v36, v37
	v_cvt_pk_f32_fp8_e32 v[36:37], v32
	v_cvt_pk_f32_fp8_sdwa v[32:33], v33 src0_sel:WORD_1
	v_pk_fma_f32 v[36:37], v[36:37], v[158:159], 0 op_sel_hi:[1,1,0]
	s_nop 0
	v_pk_fma_f32 v[36:37], v[38:39], v[160:161], v[36:37]
	v_cvt_pk_f32_fp8_sdwa v[38:39], v34 src0_sel:WORD_1
	v_pk_fma_f32 v[36:37], v[40:41], v[162:163], v[36:37]
	v_cvt_pk_f32_fp8_e32 v[40:41], v35
	v_pk_fma_f32 v[32:33], v[32:33], v[164:165], v[36:37]
	v_cvt_pk_f32_fp8_e32 v[36:37], v34
	v_cvt_pk_f32_fp8_sdwa v[34:35], v35 src0_sel:WORD_1
	v_pk_fma_f32 v[32:33], v[36:37], v[140:141], v[32:33]
	s_nop 0
	v_pk_fma_f32 v[32:33], v[38:39], v[136:137], v[32:33]
	v_cvt_pk_f32_fp8_e32 v[36:37], v29
	v_pk_fma_f32 v[32:33], v[40:41], v[142:143], v[32:33]
	s_nop 0
	v_pk_fma_f32 v[32:33], v[34:35], v[138:139], v[32:33]
	v_cvt_pk_f32_fp8_sdwa v[34:35], v28 src0_sel:WORD_1
	v_add_f32_e32 v38, v32, v33
	v_cvt_pk_f32_fp8_e32 v[32:33], v28
	v_cvt_pk_f32_fp8_sdwa v[28:29], v29 src0_sel:WORD_1
	v_pk_fma_f32 v[32:33], v[32:33], v[158:159], 0 op_sel_hi:[1,1,0]
	s_nop 0
	v_pk_fma_f32 v[32:33], v[34:35], v[160:161], v[32:33]
	v_cvt_pk_f32_fp8_sdwa v[34:35], v30 src0_sel:WORD_1
	v_pk_fma_f32 v[32:33], v[36:37], v[162:163], v[32:33]
	v_cvt_pk_f32_fp8_e32 v[36:37], v31
	v_pk_fma_f32 v[28:29], v[28:29], v[164:165], v[32:33]
	v_cvt_pk_f32_fp8_e32 v[32:33], v30
	v_cvt_pk_f32_fp8_sdwa v[30:31], v31 src0_sel:WORD_1
	v_pk_fma_f32 v[28:29], v[32:33], v[140:141], v[28:29]
	s_nop 0
	v_pk_fma_f32 v[28:29], v[34:35], v[136:137], v[28:29]
	v_cvt_pk_f32_fp8_e32 v[32:33], v25
	v_pk_fma_f32 v[28:29], v[36:37], v[142:143], v[28:29]
	s_nop 0
	v_pk_fma_f32 v[28:29], v[30:31], v[138:139], v[28:29]
	v_cvt_pk_f32_fp8_sdwa v[30:31], v24 src0_sel:WORD_1
	v_add_f32_e32 v34, v28, v29
	v_cvt_pk_f32_fp8_e32 v[28:29], v24
	v_cvt_pk_f32_fp8_sdwa v[24:25], v25 src0_sel:WORD_1
	v_pk_fma_f32 v[28:29], v[28:29], v[158:159], 0 op_sel_hi:[1,1,0]
	s_nop 0
	v_pk_fma_f32 v[28:29], v[30:31], v[160:161], v[28:29]
	v_cvt_pk_f32_fp8_sdwa v[30:31], v26 src0_sel:WORD_1
	v_pk_fma_f32 v[28:29], v[32:33], v[162:163], v[28:29]
	v_cvt_pk_f32_fp8_e32 v[32:33], v27
	v_pk_fma_f32 v[24:25], v[24:25], v[164:165], v[28:29]
	v_cvt_pk_f32_fp8_e32 v[28:29], v26
	v_cvt_pk_f32_fp8_sdwa v[26:27], v27 src0_sel:WORD_1
	v_pk_fma_f32 v[24:25], v[28:29], v[140:141], v[24:25]
	s_nop 0
	v_pk_fma_f32 v[24:25], v[30:31], v[136:137], v[24:25]
	v_cvt_pk_f32_fp8_e32 v[28:29], v21
	v_pk_fma_f32 v[24:25], v[32:33], v[142:143], v[24:25]
	s_nop 0
	v_pk_fma_f32 v[24:25], v[26:27], v[138:139], v[24:25]
	v_cvt_pk_f32_fp8_sdwa v[26:27], v20 src0_sel:WORD_1
	v_add_f32_e32 v30, v24, v25
	v_cvt_pk_f32_fp8_e32 v[24:25], v20
	v_cvt_pk_f32_fp8_sdwa v[20:21], v21 src0_sel:WORD_1
	v_pk_fma_f32 v[24:25], v[24:25], v[158:159], 0 op_sel_hi:[1,1,0]
	s_nop 0
	v_pk_fma_f32 v[24:25], v[26:27], v[160:161], v[24:25]
	v_cvt_pk_f32_fp8_sdwa v[26:27], v22 src0_sel:WORD_1
	v_pk_fma_f32 v[24:25], v[28:29], v[162:163], v[24:25]
	v_cvt_pk_f32_fp8_e32 v[28:29], v23
	v_pk_fma_f32 v[20:21], v[20:21], v[164:165], v[24:25]
	v_cvt_pk_f32_fp8_e32 v[24:25], v22
	v_cvt_pk_f32_fp8_sdwa v[22:23], v23 src0_sel:WORD_1
	v_pk_fma_f32 v[20:21], v[24:25], v[140:141], v[20:21]
	s_nop 0
	v_pk_fma_f32 v[20:21], v[26:27], v[136:137], v[20:21]
	v_cvt_pk_f32_fp8_e32 v[24:25], v17
	v_pk_fma_f32 v[20:21], v[28:29], v[142:143], v[20:21]
	s_nop 0
	v_pk_fma_f32 v[20:21], v[22:23], v[138:139], v[20:21]
	v_cvt_pk_f32_fp8_sdwa v[22:23], v16 src0_sel:WORD_1
	v_add_f32_e32 v26, v20, v21
	v_cvt_pk_f32_fp8_e32 v[20:21], v16
	v_cvt_pk_f32_fp8_sdwa v[16:17], v17 src0_sel:WORD_1
	v_pk_fma_f32 v[20:21], v[20:21], v[158:159], 0 op_sel_hi:[1,1,0]
	s_nop 0
	v_pk_fma_f32 v[20:21], v[22:23], v[160:161], v[20:21]
	v_cvt_pk_f32_fp8_sdwa v[22:23], v18 src0_sel:WORD_1
	v_pk_fma_f32 v[20:21], v[24:25], v[162:163], v[20:21]
	v_cvt_pk_f32_fp8_e32 v[24:25], v19
	v_pk_fma_f32 v[16:17], v[16:17], v[164:165], v[20:21]
	v_cvt_pk_f32_fp8_e32 v[20:21], v18
	v_cvt_pk_f32_fp8_sdwa v[18:19], v19 src0_sel:WORD_1
	v_pk_fma_f32 v[16:17], v[20:21], v[140:141], v[16:17]
	s_nop 0
	v_pk_fma_f32 v[16:17], v[22:23], v[136:137], v[16:17]
	v_cvt_pk_f32_fp8_e32 v[20:21], v13
	v_pk_fma_f32 v[16:17], v[24:25], v[142:143], v[16:17]
	s_nop 0
	v_pk_fma_f32 v[16:17], v[18:19], v[138:139], v[16:17]
	v_cvt_pk_f32_fp8_sdwa v[18:19], v12 src0_sel:WORD_1
	v_add_f32_e32 v22, v16, v17
	v_cvt_pk_f32_fp8_e32 v[16:17], v12
	v_cvt_pk_f32_fp8_sdwa v[12:13], v13 src0_sel:WORD_1
	v_pk_fma_f32 v[16:17], v[16:17], v[158:159], 0 op_sel_hi:[1,1,0]
	s_nop 0
	v_pk_fma_f32 v[16:17], v[18:19], v[160:161], v[16:17]
	v_cvt_pk_f32_fp8_sdwa v[18:19], v14 src0_sel:WORD_1
	v_pk_fma_f32 v[16:17], v[20:21], v[162:163], v[16:17]
	v_cvt_pk_f32_fp8_e32 v[20:21], v15
	v_pk_fma_f32 v[12:13], v[12:13], v[164:165], v[16:17]
	v_cvt_pk_f32_fp8_e32 v[16:17], v14
	v_cvt_pk_f32_fp8_sdwa v[14:15], v15 src0_sel:WORD_1
	v_pk_fma_f32 v[12:13], v[16:17], v[140:141], v[12:13]
	s_nop 0
	v_pk_fma_f32 v[12:13], v[18:19], v[136:137], v[12:13]
	v_cvt_pk_f32_fp8_e32 v[16:17], v9
	v_pk_fma_f32 v[12:13], v[20:21], v[142:143], v[12:13]
	s_nop 0
	v_pk_fma_f32 v[12:13], v[14:15], v[138:139], v[12:13]
	v_cvt_pk_f32_fp8_sdwa v[14:15], v8 src0_sel:WORD_1
	v_add_f32_e32 v18, v12, v13
	v_cvt_pk_f32_fp8_e32 v[12:13], v8
	v_cvt_pk_f32_fp8_sdwa v[8:9], v9 src0_sel:WORD_1
	v_pk_fma_f32 v[12:13], v[12:13], v[158:159], 0 op_sel_hi:[1,1,0]
	s_nop 0
	v_pk_fma_f32 v[12:13], v[14:15], v[160:161], v[12:13]
	v_cvt_pk_f32_fp8_sdwa v[14:15], v10 src0_sel:WORD_1
	v_pk_fma_f32 v[12:13], v[16:17], v[162:163], v[12:13]
	v_cvt_pk_f32_fp8_e32 v[16:17], v11
	v_pk_fma_f32 v[8:9], v[8:9], v[164:165], v[12:13]
	v_cvt_pk_f32_fp8_e32 v[12:13], v10
	v_cvt_pk_f32_fp8_sdwa v[10:11], v11 src0_sel:WORD_1
	v_pk_fma_f32 v[8:9], v[12:13], v[140:141], v[8:9]
	s_nop 0
	v_pk_fma_f32 v[8:9], v[14:15], v[136:137], v[8:9]
	v_cvt_pk_f32_fp8_e32 v[12:13], v5
	v_pk_fma_f32 v[8:9], v[16:17], v[142:143], v[8:9]
	s_nop 0
	v_pk_fma_f32 v[8:9], v[10:11], v[138:139], v[8:9]
	v_cvt_pk_f32_fp8_sdwa v[10:11], v4 src0_sel:WORD_1
	v_add_f32_e32 v14, v8, v9
	v_cvt_pk_f32_fp8_e32 v[8:9], v4
	v_cvt_pk_f32_fp8_sdwa v[4:5], v5 src0_sel:WORD_1
	v_pk_fma_f32 v[8:9], v[8:9], v[158:159], 0 op_sel_hi:[1,1,0]
	s_nop 0
	v_pk_fma_f32 v[8:9], v[10:11], v[160:161], v[8:9]
	v_cvt_pk_f32_fp8_sdwa v[10:11], v6 src0_sel:WORD_1
	v_pk_fma_f32 v[8:9], v[12:13], v[162:163], v[8:9]
	v_cvt_pk_f32_fp8_e32 v[12:13], v7
	v_pk_fma_f32 v[4:5], v[4:5], v[164:165], v[8:9]
	v_cvt_pk_f32_fp8_e32 v[8:9], v6
	v_cvt_pk_f32_fp8_sdwa v[6:7], v7 src0_sel:WORD_1
	v_pk_fma_f32 v[4:5], v[8:9], v[140:141], v[4:5]
	s_nop 0
	v_pk_fma_f32 v[4:5], v[10:11], v[136:137], v[4:5]
	v_cvt_pk_f32_fp8_e32 v[8:9], v1
	v_pk_fma_f32 v[4:5], v[12:13], v[142:143], v[4:5]
	s_nop 0
	v_pk_fma_f32 v[4:5], v[6:7], v[138:139], v[4:5]
	v_cvt_pk_f32_fp8_sdwa v[6:7], v0 src0_sel:WORD_1
	v_add_f32_e32 v10, v4, v5
	v_cvt_pk_f32_fp8_e32 v[4:5], v0
	v_cvt_pk_f32_fp8_sdwa v[0:1], v1 src0_sel:WORD_1
	v_pk_fma_f32 v[4:5], v[4:5], v[158:159], 0 op_sel_hi:[1,1,0]
	s_nop 0
	v_pk_fma_f32 v[4:5], v[6:7], v[160:161], v[4:5]
	v_cvt_pk_f32_fp8_sdwa v[6:7], v2 src0_sel:WORD_1
	v_pk_fma_f32 v[4:5], v[8:9], v[162:163], v[4:5]
	v_cvt_pk_f32_fp8_e32 v[8:9], v3
	v_pk_fma_f32 v[0:1], v[0:1], v[164:165], v[4:5]
	v_cvt_pk_f32_fp8_e32 v[4:5], v2
	v_cvt_pk_f32_fp8_sdwa v[2:3], v3 src0_sel:WORD_1
	v_pk_fma_f32 v[0:1], v[4:5], v[140:141], v[0:1]
	s_nop 0
	v_pk_fma_f32 v[0:1], v[6:7], v[136:137], v[0:1]
	s_nop 0
	v_pk_fma_f32 v[0:1], v[8:9], v[142:143], v[0:1]
	s_nop 0
	v_pk_fma_f32 v[0:1], v[2:3], v[138:139], v[0:1]
	v_add_f32_e32 v0, v0, v1
	s_nop 1
	v_add_f32_dpp v1, v157, v157 row_shl:4 row_mask:0xf bank_mask:0x5
	s_nop 1
	v_add_f32_dpp v1, v34, v34 row_shr:4 row_mask:0xf bank_mask:0xa
	s_waitcnt lgkmcnt(2)
	s_nop 1
	v_add_f32_dpp v2, v62, v62 row_shl:4 row_mask:0xf bank_mask:0x5
	s_nop 1
	v_add_f32_dpp v2, v30, v30 row_shr:4 row_mask:0xf bank_mask:0xa
	s_waitcnt lgkmcnt(1)
	s_nop 1
	v_add_f32_dpp v3, v58, v58 row_shl:4 row_mask:0xf bank_mask:0x5
	s_nop 1
	v_add_f32_dpp v3, v26, v26 row_shr:4 row_mask:0xf bank_mask:0xa
	s_nop 1
	v_add_f32_dpp v4, v54, v54 row_shl:4 row_mask:0xf bank_mask:0x5
	s_nop 1
	v_add_f32_dpp v4, v22, v22 row_shr:4 row_mask:0xf bank_mask:0xa
	s_waitcnt lgkmcnt(1)
	s_nop 1
	v_add_f32_dpp v5, v50, v50 row_shl:4 row_mask:0xf bank_mask:0x5
	s_nop 1
	v_add_f32_dpp v5, v18, v18 row_shr:4 row_mask:0xf bank_mask:0xa
	s_nop 1
	v_add_f32_dpp v6, v46, v46 row_shl:4 row_mask:0xf bank_mask:0x5
	s_nop 1
	v_add_f32_dpp v6, v14, v14 row_shr:4 row_mask:0xf bank_mask:0xa
	s_waitcnt lgkmcnt(0)
	s_nop 1
	v_add_f32_dpp v7, v42, v42 row_shl:4 row_mask:0xf bank_mask:0x5
	s_nop 1
	v_add_f32_dpp v7, v10, v10 row_shr:4 row_mask:0xf bank_mask:0xa
	s_nop 1
	v_add_f32_dpp v0, v0, v0 row_shr:4 row_mask:0xf bank_mask:0xa
	s_nop 1
	v_add_f32_dpp v0, v38, v38 row_shl:4 row_mask:0xf bank_mask:0x5
	s_waitcnt lgkmcnt(1)
	s_waitcnt lgkmcnt(0)
	s_nop 1
	v_add_f32_dpp v10, v1, v1 quad_perm:[2,3,0,1] row_mask:0xf bank_mask:0xf
	v_add_f32_dpp v1, v5, v5 quad_perm:[2,3,0,1] row_mask:0xf bank_mask:0xf
	v_cndmask_b32_e64 v1, v1, v10, s[6:7]
	s_nop 1
	v_add_f32_dpp v5, v2, v2 quad_perm:[2,3,0,1] row_mask:0xf bank_mask:0xf
	v_add_f32_dpp v2, v6, v6 quad_perm:[2,3,0,1] row_mask:0xf bank_mask:0xf
	v_cndmask_b32_e64 v2, v2, v5, s[6:7]
	s_nop 1
	v_add_f32_dpp v6, v3, v3 quad_perm:[2,3,0,1] row_mask:0xf bank_mask:0xf
	v_add_f32_dpp v3, v7, v7 quad_perm:[2,3,0,1] row_mask:0xf bank_mask:0xf
	v_cndmask_b32_e64 v3, v3, v6, s[6:7]
	s_nop 1
	v_add_f32_dpp v8, v4, v4 quad_perm:[2,3,0,1] row_mask:0xf bank_mask:0xf
	v_add_f32_dpp v0, v0, v0 quad_perm:[2,3,0,1] row_mask:0xf bank_mask:0xf
	v_cndmask_b32_e64 v0, v0, v8, s[6:7]
	s_waitcnt lgkmcnt(3)
	s_waitcnt lgkmcnt(2)
	s_waitcnt lgkmcnt(1)
	s_waitcnt lgkmcnt(0)
	v_mov_b32_e32 v157, v149
	s_nop 1
	v_add_f32_dpp v4, v1, v1 quad_perm:[1,0,3,2] row_mask:0xf bank_mask:0xf
	v_add_f32_dpp v3, v3, v3 quad_perm:[1,0,3,2] row_mask:0xf bank_mask:0xf
	v_cndmask_b32_e64 v3, v3, v4, s[8:9]
	s_nop 1
	v_add_f32_dpp v5, v2, v2 quad_perm:[1,0,3,2] row_mask:0xf bank_mask:0xf
	v_add_f32_dpp v2, v0, v0 quad_perm:[1,0,3,2] row_mask:0xf bank_mask:0xf
	v_cndmask_b32_e64 v2, v2, v5, s[8:9]
	s_waitcnt lgkmcnt(1)
	s_waitcnt lgkmcnt(0)
	s_waitcnt vmcnt(1)
	ds_bpermute_b32 v4, v147, v181
	v_lshl_add_u64 v[0:1], v[156:157], 2, v[154:155]
	ds_bpermute_b32 v5, v170, v181
	global_store_dword v[0:1], v3, off
	global_store_dword v[0:1], v2, off offset:32
	ds_bpermute_b32 v1, v171, v181
	s_waitcnt lgkmcnt(2)
	v_lshl_or_b32 v0, v4, 11, v145
	ds_bpermute_b32 v3, v172, v181
	s_waitcnt lgkmcnt(2)
	v_lshl_or_b32 v2, v5, 11, v145
	global_load_dwordx4 v[60:63], v0, s[16:17]
	global_load_dwordx4 v[56:59], v2, s[16:17]
	s_waitcnt lgkmcnt(1)
	v_lshl_or_b32 v0, v1, 11, v145
	ds_bpermute_b32 v1, v173, v181
	s_waitcnt lgkmcnt(1)
	v_lshl_or_b32 v2, v3, 11, v145
	ds_bpermute_b32 v3, v174, v181
	global_load_dwordx4 v[52:55], v0, s[16:17]
	global_load_dwordx4 v[48:51], v2, s[16:17]
	v_lshlrev_b64 v[136:137], 11, v[148:149]
	s_waitcnt lgkmcnt(1)
	v_lshl_or_b32 v0, v1, 11, v145
	ds_bpermute_b32 v1, v175, v181
	s_waitcnt lgkmcnt(1)
	v_lshl_or_b32 v2, v3, 11, v145
	ds_bpermute_b32 v3, v176, v181
	global_load_dwordx4 v[44:47], v0, s[16:17]
	global_load_dwordx4 v[40:43], v2, s[16:17]
	v_cndmask_b32_e64 v148, v146, v166, s[12:13]
	s_waitcnt lgkmcnt(1)
	v_lshl_or_b32 v0, v1, 11, v145
	s_waitcnt vmcnt(8)
	ds_bpermute_b32 v1, v147, v167
	s_waitcnt lgkmcnt(1)
	v_lshl_or_b32 v2, v3, 11, v145
	ds_bpermute_b32 v3, v170, v167
	global_load_dwordx4 v[36:39], v0, s[16:17]
	global_load_dwordx4 v[32:35], v2, s[16:17]
	v_lshlrev_b64 v[158:159], 9, v[148:149]
	s_waitcnt lgkmcnt(1)
	v_lshl_or_b32 v0, v1, 11, v145
	ds_bpermute_b32 v1, v171, v167
	s_waitcnt lgkmcnt(1)
	v_lshl_or_b32 v2, v3, 11, v145
	ds_bpermute_b32 v3, v172, v167
	global_load_dwordx4 v[28:31], v0, s[16:17]
	global_load_dwordx4 v[24:27], v2, s[16:17]
	v_lshl_add_u64 v[140:141], v[150:151], 0, v[136:137]
	s_waitcnt lgkmcnt(1)
	v_lshl_or_b32 v0, v1, 11, v145
	ds_bpermute_b32 v1, v173, v167
	s_waitcnt lgkmcnt(1)
	v_lshl_or_b32 v2, v3, 11, v145
	ds_bpermute_b32 v3, v174, v167
	global_load_dwordx4 v[20:23], v0, s[16:17]
	global_load_dwordx4 v[16:19], v2, s[16:17]
	ds_bpermute_b32 v2, v176, v167
	s_waitcnt lgkmcnt(2)
	v_lshl_or_b32 v0, v1, 11, v145
	ds_bpermute_b32 v1, v175, v167
	s_waitcnt lgkmcnt(2)
	v_lshl_or_b32 v3, v3, 11, v145
	global_load_dwordx4 v[12:15], v0, s[16:17]
	global_load_dwordx4 v[8:11], v3, s[16:17]
	v_lshl_add_u64 v[158:159], v[152:153], 0, v[158:159]
	s_waitcnt lgkmcnt(0)
	v_lshl_or_b32 v0, v1, 11, v145
	v_lshl_or_b32 v1, v2, 11, v145
	global_load_dwordx4 v[4:7], v0, s[16:17]
	s_nop 0
	global_load_dwordx4 v[0:3], v1, s[16:17]
	s_nop 0
	global_load_dwordx4 v[136:139], v[140:141], off offset:16
	s_nop 0
	global_load_dwordx4 v[140:143], v[140:141], off
	s_nop 0
	global_load_dword v181, v[158:159], off
	global_load_dword v157, v[158:159], off offset:256
	s_and_saveexec_b64 s[12:13], s[10:11]
	s_cbranch_execz .LBB0_912
	v_lshlrev_b32_e32 v158, 16, v135
	v_and_b32_e32 v159, 0xffff0000, v135
	v_lshlrev_b32_e32 v160, 16, v134
	v_and_b32_e32 v161, 0xffff0000, v134
	v_lshlrev_b32_e32 v134, 16, v133
	v_and_b32_e32 v135, 0xffff0000, v133
	v_lshlrev_b32_e32 v162, 16, v132
	v_and_b32_e32 v163, 0xffff0000, v132
	v_lshlrev_b32_e32 v132, 16, v131
	v_and_b32_e32 v133, 0xffff0000, v131
	v_lshlrev_b32_e32 v164, 16, v130
	v_and_b32_e32 v165, 0xffff0000, v130
	v_lshlrev_b32_e32 v130, 16, v129
	v_and_b32_e32 v131, 0xffff0000, v129
	v_lshlrev_b32_e32 v166, 16, v128
	v_and_b32_e32 v167, 0xffff0000, v128
	v_cvt_pk_f32_fp8_e32 v[128:129], v124
	v_cvt_pk_f32_fp8_sdwa v[182:183], v124 src0_sel:WORD_1
	v_cvt_pk_f32_fp8_e32 v[184:185], v125
	v_cvt_pk_f32_fp8_sdwa v[124:125], v125 src0_sel:WORD_1
	v_pk_fma_f32 v[128:129], v[128:129], v[166:167], 0 op_sel_hi:[1,1,0]
	s_nop 0
	v_pk_fma_f32 v[128:129], v[182:183], v[130:131], v[128:129]
	v_cvt_pk_f32_fp8_sdwa v[182:183], v126 src0_sel:WORD_1
	v_pk_fma_f32 v[128:129], v[184:185], v[164:165], v[128:129]
	v_cvt_pk_f32_fp8_e32 v[184:185], v127
	v_pk_fma_f32 v[124:125], v[124:125], v[132:133], v[128:129]
	v_cvt_pk_f32_fp8_e32 v[128:129], v126
	v_cvt_pk_f32_fp8_sdwa v[126:127], v127 src0_sel:WORD_1
	v_pk_fma_f32 v[124:125], v[128:129], v[162:163], v[124:125]
	s_nop 0
	v_pk_fma_f32 v[124:125], v[182:183], v[134:135], v[124:125]
	v_cvt_pk_f32_fp8_e32 v[128:129], v121
	v_pk_fma_f32 v[124:125], v[184:185], v[160:161], v[124:125]
	s_nop 0
	v_pk_fma_f32 v[124:125], v[126:127], v[158:159], v[124:125]
	v_cvt_pk_f32_fp8_sdwa v[126:127], v120 src0_sel:WORD_1
	v_add_f32_e32 v148, v124, v125
	v_cvt_pk_f32_fp8_e32 v[124:125], v120
	v_cvt_pk_f32_fp8_sdwa v[120:121], v121 src0_sel:WORD_1
	v_pk_fma_f32 v[124:125], v[124:125], v[166:167], 0 op_sel_hi:[1,1,0]
	s_nop 0
	v_pk_fma_f32 v[124:125], v[126:127], v[130:131], v[124:125]
	v_cvt_pk_f32_fp8_sdwa v[126:127], v122 src0_sel:WORD_1
	v_pk_fma_f32 v[124:125], v[128:129], v[164:165], v[124:125]
	v_cvt_pk_f32_fp8_e32 v[128:129], v123
	v_pk_fma_f32 v[120:121], v[120:121], v[132:133], v[124:125]
	v_cvt_pk_f32_fp8_e32 v[124:125], v122
	v_cvt_pk_f32_fp8_sdwa v[122:123], v123 src0_sel:WORD_1
	v_pk_fma_f32 v[120:121], v[124:125], v[162:163], v[120:121]
	s_nop 0
	v_pk_fma_f32 v[120:121], v[126:127], v[134:135], v[120:121]
	v_cvt_pk_f32_fp8_e32 v[124:125], v117
	v_pk_fma_f32 v[120:121], v[128:129], v[160:161], v[120:121]
	s_nop 0
	v_pk_fma_f32 v[120:121], v[122:123], v[158:159], v[120:121]
	v_cvt_pk_f32_fp8_sdwa v[122:123], v116 src0_sel:WORD_1
	v_add_f32_e32 v126, v120, v121
	v_cvt_pk_f32_fp8_e32 v[120:121], v116
	v_cvt_pk_f32_fp8_sdwa v[116:117], v117 src0_sel:WORD_1
	v_pk_fma_f32 v[120:121], v[120:121], v[166:167], 0 op_sel_hi:[1,1,0]
	s_nop 0
	v_pk_fma_f32 v[120:121], v[122:123], v[130:131], v[120:121]
	v_cvt_pk_f32_fp8_sdwa v[122:123], v118 src0_sel:WORD_1
	v_pk_fma_f32 v[120:121], v[124:125], v[164:165], v[120:121]
	v_cvt_pk_f32_fp8_e32 v[124:125], v119
	v_pk_fma_f32 v[116:117], v[116:117], v[132:133], v[120:121]
	v_cvt_pk_f32_fp8_e32 v[120:121], v118
	v_cvt_pk_f32_fp8_sdwa v[118:119], v119 src0_sel:WORD_1
	v_pk_fma_f32 v[116:117], v[120:121], v[162:163], v[116:117]
	s_nop 0
	v_pk_fma_f32 v[116:117], v[122:123], v[134:135], v[116:117]
	v_cvt_pk_f32_fp8_e32 v[120:121], v113
	v_pk_fma_f32 v[116:117], v[124:125], v[160:161], v[116:117]
	s_nop 0
	v_pk_fma_f32 v[116:117], v[118:119], v[158:159], v[116:117]
	v_cvt_pk_f32_fp8_sdwa v[118:119], v112 src0_sel:WORD_1
	v_add_f32_e32 v122, v116, v117
	v_cvt_pk_f32_fp8_e32 v[116:117], v112
	v_cvt_pk_f32_fp8_sdwa v[112:113], v113 src0_sel:WORD_1
	v_pk_fma_f32 v[116:117], v[116:117], v[166:167], 0 op_sel_hi:[1,1,0]
	s_nop 0
	v_pk_fma_f32 v[116:117], v[118:119], v[130:131], v[116:117]
	v_cvt_pk_f32_fp8_sdwa v[118:119], v114 src0_sel:WORD_1
	v_pk_fma_f32 v[116:117], v[120:121], v[164:165], v[116:117]
	v_cvt_pk_f32_fp8_e32 v[120:121], v115
	v_pk_fma_f32 v[112:113], v[112:113], v[132:133], v[116:117]
	v_cvt_pk_f32_fp8_e32 v[116:117], v114
	v_cvt_pk_f32_fp8_sdwa v[114:115], v115 src0_sel:WORD_1
	v_pk_fma_f32 v[112:113], v[116:117], v[162:163], v[112:113]
	s_nop 0
	v_pk_fma_f32 v[112:113], v[118:119], v[134:135], v[112:113]
	v_cvt_pk_f32_fp8_e32 v[116:117], v109
	v_pk_fma_f32 v[112:113], v[120:121], v[160:161], v[112:113]
	s_nop 0
	v_pk_fma_f32 v[112:113], v[114:115], v[158:159], v[112:113]
	v_cvt_pk_f32_fp8_sdwa v[114:115], v108 src0_sel:WORD_1
	v_add_f32_e32 v118, v112, v113
	v_cvt_pk_f32_fp8_e32 v[112:113], v108
	v_cvt_pk_f32_fp8_sdwa v[108:109], v109 src0_sel:WORD_1
	v_pk_fma_f32 v[112:113], v[112:113], v[166:167], 0 op_sel_hi:[1,1,0]
	s_nop 0
	v_pk_fma_f32 v[112:113], v[114:115], v[130:131], v[112:113]
	v_cvt_pk_f32_fp8_sdwa v[114:115], v110 src0_sel:WORD_1
	v_pk_fma_f32 v[112:113], v[116:117], v[164:165], v[112:113]
	v_cvt_pk_f32_fp8_e32 v[116:117], v111
	v_pk_fma_f32 v[108:109], v[108:109], v[132:133], v[112:113]
	v_cvt_pk_f32_fp8_e32 v[112:113], v110
	v_cvt_pk_f32_fp8_sdwa v[110:111], v111 src0_sel:WORD_1
	v_pk_fma_f32 v[108:109], v[112:113], v[162:163], v[108:109]
	s_nop 0
	v_pk_fma_f32 v[108:109], v[114:115], v[134:135], v[108:109]
	v_cvt_pk_f32_fp8_e32 v[112:113], v105
	v_pk_fma_f32 v[108:109], v[116:117], v[160:161], v[108:109]
	s_nop 0
	v_pk_fma_f32 v[108:109], v[110:111], v[158:159], v[108:109]
	v_cvt_pk_f32_fp8_sdwa v[110:111], v104 src0_sel:WORD_1
	v_add_f32_e32 v114, v108, v109
	v_cvt_pk_f32_fp8_e32 v[108:109], v104
	v_cvt_pk_f32_fp8_sdwa v[104:105], v105 src0_sel:WORD_1
	v_pk_fma_f32 v[108:109], v[108:109], v[166:167], 0 op_sel_hi:[1,1,0]
	s_nop 0
	v_pk_fma_f32 v[108:109], v[110:111], v[130:131], v[108:109]
	v_cvt_pk_f32_fp8_sdwa v[110:111], v106 src0_sel:WORD_1
	v_pk_fma_f32 v[108:109], v[112:113], v[164:165], v[108:109]
	v_cvt_pk_f32_fp8_e32 v[112:113], v107
	v_pk_fma_f32 v[104:105], v[104:105], v[132:133], v[108:109]
	v_cvt_pk_f32_fp8_e32 v[108:109], v106
	v_cvt_pk_f32_fp8_sdwa v[106:107], v107 src0_sel:WORD_1
	v_pk_fma_f32 v[104:105], v[108:109], v[162:163], v[104:105]
	s_nop 0
	v_pk_fma_f32 v[104:105], v[110:111], v[134:135], v[104:105]
	v_cvt_pk_f32_fp8_e32 v[108:109], v101
	v_pk_fma_f32 v[104:105], v[112:113], v[160:161], v[104:105]
	s_nop 0
	v_pk_fma_f32 v[104:105], v[106:107], v[158:159], v[104:105]
	v_cvt_pk_f32_fp8_sdwa v[106:107], v100 src0_sel:WORD_1
	v_add_f32_e32 v110, v104, v105
	v_cvt_pk_f32_fp8_e32 v[104:105], v100
	v_cvt_pk_f32_fp8_sdwa v[100:101], v101 src0_sel:WORD_1
	v_pk_fma_f32 v[104:105], v[104:105], v[166:167], 0 op_sel_hi:[1,1,0]
	s_nop 0
	v_pk_fma_f32 v[104:105], v[106:107], v[130:131], v[104:105]
	v_cvt_pk_f32_fp8_sdwa v[106:107], v102 src0_sel:WORD_1
	v_pk_fma_f32 v[104:105], v[108:109], v[164:165], v[104:105]
	v_cvt_pk_f32_fp8_e32 v[108:109], v103
	v_pk_fma_f32 v[100:101], v[100:101], v[132:133], v[104:105]
	v_cvt_pk_f32_fp8_e32 v[104:105], v102
	v_cvt_pk_f32_fp8_sdwa v[102:103], v103 src0_sel:WORD_1
	v_pk_fma_f32 v[100:101], v[104:105], v[162:163], v[100:101]
	s_nop 0
	v_pk_fma_f32 v[100:101], v[106:107], v[134:135], v[100:101]
	v_cvt_pk_f32_fp8_e32 v[104:105], v97
	v_pk_fma_f32 v[100:101], v[108:109], v[160:161], v[100:101]
	s_nop 0
	v_pk_fma_f32 v[100:101], v[102:103], v[158:159], v[100:101]
	v_cvt_pk_f32_fp8_sdwa v[102:103], v96 src0_sel:WORD_1
	v_add_f32_e32 v106, v100, v101
	v_cvt_pk_f32_fp8_e32 v[100:101], v96
	v_cvt_pk_f32_fp8_sdwa v[96:97], v97 src0_sel:WORD_1
	v_pk_fma_f32 v[100:101], v[100:101], v[166:167], 0 op_sel_hi:[1,1,0]
	s_nop 0
	v_pk_fma_f32 v[100:101], v[102:103], v[130:131], v[100:101]
	v_cvt_pk_f32_fp8_sdwa v[102:103], v98 src0_sel:WORD_1
	v_pk_fma_f32 v[100:101], v[104:105], v[164:165], v[100:101]
	v_cvt_pk_f32_fp8_e32 v[104:105], v99
	v_pk_fma_f32 v[96:97], v[96:97], v[132:133], v[100:101]
	v_cvt_pk_f32_fp8_e32 v[100:101], v98
	v_cvt_pk_f32_fp8_sdwa v[98:99], v99 src0_sel:WORD_1
	v_pk_fma_f32 v[96:97], v[100:101], v[162:163], v[96:97]
	s_nop 0
	v_pk_fma_f32 v[96:97], v[102:103], v[134:135], v[96:97]
	v_cvt_pk_f32_fp8_e32 v[100:101], v93
	v_pk_fma_f32 v[96:97], v[104:105], v[160:161], v[96:97]
	s_nop 0
	v_pk_fma_f32 v[96:97], v[98:99], v[158:159], v[96:97]
	v_cvt_pk_f32_fp8_sdwa v[98:99], v92 src0_sel:WORD_1
	v_add_f32_e32 v102, v96, v97
	v_cvt_pk_f32_fp8_e32 v[96:97], v92
	v_cvt_pk_f32_fp8_sdwa v[92:93], v93 src0_sel:WORD_1
	v_pk_fma_f32 v[96:97], v[96:97], v[166:167], 0 op_sel_hi:[1,1,0]
	s_nop 0
	v_pk_fma_f32 v[96:97], v[98:99], v[130:131], v[96:97]
	v_cvt_pk_f32_fp8_sdwa v[98:99], v94 src0_sel:WORD_1
	v_pk_fma_f32 v[96:97], v[100:101], v[164:165], v[96:97]
	v_cvt_pk_f32_fp8_e32 v[100:101], v95
	v_pk_fma_f32 v[92:93], v[92:93], v[132:133], v[96:97]
	v_cvt_pk_f32_fp8_e32 v[96:97], v94
	v_cvt_pk_f32_fp8_sdwa v[94:95], v95 src0_sel:WORD_1
	v_pk_fma_f32 v[92:93], v[96:97], v[162:163], v[92:93]
	s_nop 0
	v_pk_fma_f32 v[92:93], v[98:99], v[134:135], v[92:93]
	v_cvt_pk_f32_fp8_e32 v[96:97], v89
	v_pk_fma_f32 v[92:93], v[100:101], v[160:161], v[92:93]
	s_nop 0
	v_pk_fma_f32 v[92:93], v[94:95], v[158:159], v[92:93]
	v_cvt_pk_f32_fp8_sdwa v[94:95], v88 src0_sel:WORD_1
	v_add_f32_e32 v98, v92, v93
	v_cvt_pk_f32_fp8_e32 v[92:93], v88
	v_cvt_pk_f32_fp8_sdwa v[88:89], v89 src0_sel:WORD_1
	v_pk_fma_f32 v[92:93], v[92:93], v[166:167], 0 op_sel_hi:[1,1,0]
	s_nop 0
	v_pk_fma_f32 v[92:93], v[94:95], v[130:131], v[92:93]
	v_cvt_pk_f32_fp8_sdwa v[94:95], v90 src0_sel:WORD_1
	v_pk_fma_f32 v[92:93], v[96:97], v[164:165], v[92:93]
	v_cvt_pk_f32_fp8_e32 v[96:97], v91
	v_pk_fma_f32 v[88:89], v[88:89], v[132:133], v[92:93]
	v_cvt_pk_f32_fp8_e32 v[92:93], v90
	v_cvt_pk_f32_fp8_sdwa v[90:91], v91 src0_sel:WORD_1
	v_pk_fma_f32 v[88:89], v[92:93], v[162:163], v[88:89]
	s_nop 0
	v_pk_fma_f32 v[88:89], v[94:95], v[134:135], v[88:89]
	v_cvt_pk_f32_fp8_e32 v[92:93], v85
	v_pk_fma_f32 v[88:89], v[96:97], v[160:161], v[88:89]
	s_nop 0
	v_pk_fma_f32 v[88:89], v[90:91], v[158:159], v[88:89]
	v_cvt_pk_f32_fp8_sdwa v[90:91], v84 src0_sel:WORD_1
	v_add_f32_e32 v94, v88, v89
	v_cvt_pk_f32_fp8_e32 v[88:89], v84
	v_cvt_pk_f32_fp8_sdwa v[84:85], v85 src0_sel:WORD_1
	v_pk_fma_f32 v[88:89], v[88:89], v[166:167], 0 op_sel_hi:[1,1,0]
	s_nop 0
	v_pk_fma_f32 v[88:89], v[90:91], v[130:131], v[88:89]
	v_cvt_pk_f32_fp8_sdwa v[90:91], v86 src0_sel:WORD_1
	v_pk_fma_f32 v[88:89], v[92:93], v[164:165], v[88:89]
	v_cvt_pk_f32_fp8_e32 v[92:93], v87
	v_pk_fma_f32 v[84:85], v[84:85], v[132:133], v[88:89]
	v_cvt_pk_f32_fp8_e32 v[88:89], v86
	v_cvt_pk_f32_fp8_sdwa v[86:87], v87 src0_sel:WORD_1
	v_pk_fma_f32 v[84:85], v[88:89], v[162:163], v[84:85]
	s_nop 0
	v_pk_fma_f32 v[84:85], v[90:91], v[134:135], v[84:85]
	v_cvt_pk_f32_fp8_e32 v[88:89], v81
	v_pk_fma_f32 v[84:85], v[92:93], v[160:161], v[84:85]
	s_nop 0
	v_pk_fma_f32 v[84:85], v[86:87], v[158:159], v[84:85]
	v_cvt_pk_f32_fp8_sdwa v[86:87], v80 src0_sel:WORD_1
	v_add_f32_e32 v90, v84, v85
	v_cvt_pk_f32_fp8_e32 v[84:85], v80
	v_cvt_pk_f32_fp8_sdwa v[80:81], v81 src0_sel:WORD_1
	v_pk_fma_f32 v[84:85], v[84:85], v[166:167], 0 op_sel_hi:[1,1,0]
	s_nop 0
	v_pk_fma_f32 v[84:85], v[86:87], v[130:131], v[84:85]
	v_cvt_pk_f32_fp8_sdwa v[86:87], v82 src0_sel:WORD_1
	v_pk_fma_f32 v[84:85], v[88:89], v[164:165], v[84:85]
	v_cvt_pk_f32_fp8_e32 v[88:89], v83
	v_pk_fma_f32 v[80:81], v[80:81], v[132:133], v[84:85]
	v_cvt_pk_f32_fp8_e32 v[84:85], v82
	v_cvt_pk_f32_fp8_sdwa v[82:83], v83 src0_sel:WORD_1
	v_pk_fma_f32 v[80:81], v[84:85], v[162:163], v[80:81]
	s_nop 0
	v_pk_fma_f32 v[80:81], v[86:87], v[134:135], v[80:81]
	v_cvt_pk_f32_fp8_e32 v[84:85], v77
	v_pk_fma_f32 v[80:81], v[88:89], v[160:161], v[80:81]
	s_nop 0
	v_pk_fma_f32 v[80:81], v[82:83], v[158:159], v[80:81]
	v_cvt_pk_f32_fp8_sdwa v[82:83], v76 src0_sel:WORD_1
	v_add_f32_e32 v86, v80, v81
	v_cvt_pk_f32_fp8_e32 v[80:81], v76
	v_cvt_pk_f32_fp8_sdwa v[76:77], v77 src0_sel:WORD_1
	v_pk_fma_f32 v[80:81], v[80:81], v[166:167], 0 op_sel_hi:[1,1,0]
	s_nop 0
	v_pk_fma_f32 v[80:81], v[82:83], v[130:131], v[80:81]
	v_cvt_pk_f32_fp8_sdwa v[82:83], v78 src0_sel:WORD_1
	v_pk_fma_f32 v[80:81], v[84:85], v[164:165], v[80:81]
	v_cvt_pk_f32_fp8_e32 v[84:85], v79
	v_pk_fma_f32 v[76:77], v[76:77], v[132:133], v[80:81]
	v_cvt_pk_f32_fp8_e32 v[80:81], v78
	v_cvt_pk_f32_fp8_sdwa v[78:79], v79 src0_sel:WORD_1
	v_pk_fma_f32 v[76:77], v[80:81], v[162:163], v[76:77]
	s_nop 0
	v_pk_fma_f32 v[76:77], v[82:83], v[134:135], v[76:77]
	v_cvt_pk_f32_fp8_e32 v[80:81], v73
	v_pk_fma_f32 v[76:77], v[84:85], v[160:161], v[76:77]
	s_nop 0
	v_pk_fma_f32 v[76:77], v[78:79], v[158:159], v[76:77]
	v_cvt_pk_f32_fp8_sdwa v[78:79], v72 src0_sel:WORD_1
	v_add_f32_e32 v82, v76, v77
	v_cvt_pk_f32_fp8_e32 v[76:77], v72
	v_cvt_pk_f32_fp8_sdwa v[72:73], v73 src0_sel:WORD_1
	v_pk_fma_f32 v[76:77], v[76:77], v[166:167], 0 op_sel_hi:[1,1,0]
	s_nop 0
	v_pk_fma_f32 v[76:77], v[78:79], v[130:131], v[76:77]
	v_cvt_pk_f32_fp8_sdwa v[78:79], v74 src0_sel:WORD_1
	v_pk_fma_f32 v[76:77], v[80:81], v[164:165], v[76:77]
	v_cvt_pk_f32_fp8_e32 v[80:81], v75
	v_pk_fma_f32 v[72:73], v[72:73], v[132:133], v[76:77]
	v_cvt_pk_f32_fp8_e32 v[76:77], v74
	v_cvt_pk_f32_fp8_sdwa v[74:75], v75 src0_sel:WORD_1
	v_pk_fma_f32 v[72:73], v[76:77], v[162:163], v[72:73]
	s_nop 0
	v_pk_fma_f32 v[72:73], v[78:79], v[134:135], v[72:73]
	v_cvt_pk_f32_fp8_e32 v[76:77], v69
	v_pk_fma_f32 v[72:73], v[80:81], v[160:161], v[72:73]
	s_nop 0
	v_pk_fma_f32 v[72:73], v[74:75], v[158:159], v[72:73]
	v_cvt_pk_f32_fp8_sdwa v[74:75], v68 src0_sel:WORD_1
	v_add_f32_e32 v78, v72, v73
	v_cvt_pk_f32_fp8_e32 v[72:73], v68
	v_cvt_pk_f32_fp8_sdwa v[68:69], v69 src0_sel:WORD_1
	v_pk_fma_f32 v[72:73], v[72:73], v[166:167], 0 op_sel_hi:[1,1,0]
	s_nop 0
	v_pk_fma_f32 v[72:73], v[74:75], v[130:131], v[72:73]
	v_cvt_pk_f32_fp8_sdwa v[74:75], v70 src0_sel:WORD_1
	v_pk_fma_f32 v[72:73], v[76:77], v[164:165], v[72:73]
	v_cvt_pk_f32_fp8_e32 v[76:77], v71
	v_pk_fma_f32 v[68:69], v[68:69], v[132:133], v[72:73]
	v_cvt_pk_f32_fp8_e32 v[72:73], v70
	v_cvt_pk_f32_fp8_sdwa v[70:71], v71 src0_sel:WORD_1
	v_pk_fma_f32 v[68:69], v[72:73], v[162:163], v[68:69]
	s_nop 0
	v_pk_fma_f32 v[68:69], v[74:75], v[134:135], v[68:69]
	v_cvt_pk_f32_fp8_e32 v[72:73], v65
	v_pk_fma_f32 v[68:69], v[76:77], v[160:161], v[68:69]
	s_nop 0
	v_pk_fma_f32 v[68:69], v[70:71], v[158:159], v[68:69]
	v_cvt_pk_f32_fp8_sdwa v[70:71], v64 src0_sel:WORD_1
	v_add_f32_e32 v74, v68, v69
	v_cvt_pk_f32_fp8_e32 v[68:69], v64
	v_cvt_pk_f32_fp8_sdwa v[64:65], v65 src0_sel:WORD_1
	v_pk_fma_f32 v[68:69], v[68:69], v[166:167], 0 op_sel_hi:[1,1,0]
	s_nop 0
	v_pk_fma_f32 v[68:69], v[70:71], v[130:131], v[68:69]
	v_cvt_pk_f32_fp8_sdwa v[70:71], v66 src0_sel:WORD_1
	v_pk_fma_f32 v[68:69], v[72:73], v[164:165], v[68:69]
	v_cvt_pk_f32_fp8_e32 v[72:73], v67
	v_pk_fma_f32 v[64:65], v[64:65], v[132:133], v[68:69]
	v_cvt_pk_f32_fp8_e32 v[68:69], v66
	v_cvt_pk_f32_fp8_sdwa v[66:67], v67 src0_sel:WORD_1
	v_pk_fma_f32 v[64:65], v[68:69], v[162:163], v[64:65]
	s_nop 0
	v_pk_fma_f32 v[64:65], v[70:71], v[134:135], v[64:65]
	s_nop 0
	v_pk_fma_f32 v[64:65], v[72:73], v[160:161], v[64:65]
	s_nop 0
	v_pk_fma_f32 v[64:65], v[66:67], v[158:159], v[64:65]
	v_add_f32_e32 v64, v64, v65
	s_nop 1
	v_add_f32_dpp v65, v148, v148 row_shl:4 row_mask:0xf bank_mask:0x5
	s_nop 1
	v_add_f32_dpp v65, v98, v98 row_shr:4 row_mask:0xf bank_mask:0xa
	s_waitcnt lgkmcnt(2)
	s_nop 1
	v_add_f32_dpp v66, v126, v126 row_shl:4 row_mask:0xf bank_mask:0x5
	s_nop 1
	v_add_f32_dpp v66, v94, v94 row_shr:4 row_mask:0xf bank_mask:0xa
	s_waitcnt lgkmcnt(1)
	s_nop 1
	v_add_f32_dpp v67, v122, v122 row_shl:4 row_mask:0xf bank_mask:0x5
	s_nop 1
	v_add_f32_dpp v67, v90, v90 row_shr:4 row_mask:0xf bank_mask:0xa
	s_nop 1
	v_add_f32_dpp v68, v118, v118 row_shl:4 row_mask:0xf bank_mask:0x5
	s_nop 1
	v_add_f32_dpp v68, v86, v86 row_shr:4 row_mask:0xf bank_mask:0xa
	s_waitcnt lgkmcnt(1)
	s_nop 1
	v_add_f32_dpp v69, v114, v114 row_shl:4 row_mask:0xf bank_mask:0x5
	s_nop 1
	v_add_f32_dpp v69, v82, v82 row_shr:4 row_mask:0xf bank_mask:0xa
	s_nop 1
	v_add_f32_dpp v70, v110, v110 row_shl:4 row_mask:0xf bank_mask:0x5
	s_nop 1
	v_add_f32_dpp v70, v78, v78 row_shr:4 row_mask:0xf bank_mask:0xa
	s_waitcnt lgkmcnt(0)
	s_nop 1
	v_add_f32_dpp v71, v106, v106 row_shl:4 row_mask:0xf bank_mask:0x5
	s_nop 1
	v_add_f32_dpp v71, v74, v74 row_shr:4 row_mask:0xf bank_mask:0xa
	s_nop 1
	v_add_f32_dpp v64, v64, v64 row_shr:4 row_mask:0xf bank_mask:0xa
	s_nop 1
	v_add_f32_dpp v64, v102, v102 row_shl:4 row_mask:0xf bank_mask:0x5
	s_waitcnt lgkmcnt(1)
	s_waitcnt lgkmcnt(0)
	s_nop 1
	v_add_f32_dpp v74, v65, v65 quad_perm:[2,3,0,1] row_mask:0xf bank_mask:0xf
	v_add_f32_dpp v65, v69, v69 quad_perm:[2,3,0,1] row_mask:0xf bank_mask:0xf
	v_cndmask_b32_e64 v65, v65, v74, s[6:7]
	s_nop 1
	v_add_f32_dpp v69, v66, v66 quad_perm:[2,3,0,1] row_mask:0xf bank_mask:0xf
	v_add_f32_dpp v66, v70, v70 quad_perm:[2,3,0,1] row_mask:0xf bank_mask:0xf
	v_cndmask_b32_e64 v66, v66, v69, s[6:7]
	s_nop 1
	v_add_f32_dpp v70, v67, v67 quad_perm:[2,3,0,1] row_mask:0xf bank_mask:0xf
	v_add_f32_dpp v67, v71, v71 quad_perm:[2,3,0,1] row_mask:0xf bank_mask:0xf
	v_cndmask_b32_e64 v67, v67, v70, s[6:7]
	s_nop 1
	v_add_f32_dpp v72, v68, v68 quad_perm:[2,3,0,1] row_mask:0xf bank_mask:0xf
	v_add_f32_dpp v64, v64, v64 quad_perm:[2,3,0,1] row_mask:0xf bank_mask:0xf
	v_cndmask_b32_e64 v64, v64, v72, s[6:7]
	s_waitcnt lgkmcnt(3)
	s_waitcnt lgkmcnt(2)
	s_waitcnt lgkmcnt(1)
	s_waitcnt lgkmcnt(0)
	v_add_u32_e32 v148, s24, v156
	s_nop 1
	v_add_f32_dpp v68, v65, v65 quad_perm:[1,0,3,2] row_mask:0xf bank_mask:0xf
	v_add_f32_dpp v67, v67, v67 quad_perm:[1,0,3,2] row_mask:0xf bank_mask:0xf
	v_cndmask_b32_e64 v67, v67, v68, s[8:9]
	s_nop 1
	v_add_f32_dpp v69, v66, v66 quad_perm:[1,0,3,2] row_mask:0xf bank_mask:0xf
	v_add_f32_dpp v66, v64, v64 quad_perm:[1,0,3,2] row_mask:0xf bank_mask:0xf
	v_cndmask_b32_e64 v66, v66, v69, s[8:9]
	s_waitcnt lgkmcnt(1)
	s_waitcnt lgkmcnt(0)
	v_lshl_add_u64 v[64:65], v[148:149], 2, v[154:155]
	global_store_dword v[64:65], v67, off
	global_store_dword v[64:65], v66, off offset:32
	s_branch .LBB0_912
